# v5 + first grid seam uses the XCD barrier instead of cg grid sync
# speedup vs baseline: 1.0215x; 1.0044x over previous
; #define LAS __attribute__((address_space(3)))
; __device__ __forceinline__ unsigned xb_xcc_id() { return (unsigned)__builtin_amdgcn_s_getreg((3 << 11) | 20) & 0xFu; }
; __device__ __forceinline__ void xcd_barrier(const XcdBarrier& b) {
;     asm volatile("s_waitcnt vmcnt(0)" ::: "memory");
;     __syncthreads();
;     if (threadIdx.x == 0) {
;         unsigned* bar = b.bar;
;         __builtin_amdgcn_s_waitcnt(0);
;         unsigned nloc = b.st[0], nx = b.st[1];
;         if (nloc == 0u) { xcd_barrier_complete(bar, b.x, nloc, nx); b.st[0] = nloc; b.st[1] = nx; }
; __global__ void __launch_bounds__(NTHR, 2) mega(Params P, int ph_lo, int ph_hi, int rep0) {
;     ...
;       run_phase(P, ph, smem, s_rs, rep + rep0, &s_item);
;       if (ph + 1 < ph_hi || rep + 1 < reps) {
;         if (first_sync) { cg::this_grid().sync(); first_sync = false; } else { XcdBarrier xb; xb.bar = (unsigned*)(P.ws + OFF_BAR); xb.x = xb_xcc_id(); xb.st = (volatile LAS unsigned*)&xb_words; xcd_barrier(xb); }
;       }
.LBB0_559:
	v_readlane_b32 s2, v255, 21
	v_readlane_b32 s3, v255, 22
	s_xor_b64 s[6:7], s[2:3], -1
	s_mov_b64 s[2:3], -1
	s_and_b64 vcc, exec, s[6:7]
	s_getreg_b32 s6, hwreg(HW_REG_XCC_ID, 0, 4)
	s_waitcnt vmcnt(0)
	s_waitcnt lgkmcnt(0)
	s_barrier
	s_mov_b64 s[2:3], exec
	v_readlane_b32 s8, v253, 0
	v_readlane_b32 s9, v253, 1
	s_and_b64 s[8:9], s[2:3], s[8:9]
	s_mov_b64 exec, s[8:9]
	s_cbranch_execz .LBB0_612
	v_mov_b32_e32 v0, 0x12400
	s_waitcnt vmcnt(0) expcnt(0) lgkmcnt(0)
	ds_read_b32 v3, v0
	v_mov_b32_e32 v0, 0x12404
	ds_read_b32 v2, v0
	s_and_b32 s12, s6, 15
	s_waitcnt lgkmcnt(1)
	v_cmp_ne_u32_e32 vcc, 0, v3
	s_cbranch_vccnz .LBB0_576
	v_readlane_b32 s8, v255, 23
	v_readlane_b32 s9, v255, 24
	s_load_dwordx2 s[6:7], s[8:9], 0x0
	s_nop 0
	s_load_dword s8, s[8:9], 0x8
	s_mov_b32 s14, 1
	s_waitcnt lgkmcnt(0)
	s_mul_i32 s13, s7, s6
	s_mul_i32 s13, s13, s8
	s_branch .LBB0_564
